# LN: DPP reductions + vmcnt(0) at loop heads relaxed to counted waits (stores stay in flight)
# speedup vs baseline: 1.0039x; 1.0039x over previous
; __device__ __forceinline__ float bflo(unsigned w) { return __uint_as_float(w << 16); }
; __device__ __forceinline__ float bfhi(unsigned w) { return __uint_as_float(w & 0xffff0000u); }
; __device__ __forceinline__ void ln_panel_b(bf16_t* hb, float* outf, const float* gam, const float* bet) {
;     int tid_ = threadIdx.x; asm volatile("" : "+v"(tid_));
;     const int lane = tid_ & 63, wave = __builtin_amdgcn_readfirstlane(tid_ >> 6);
;     constexpr int NB = 2;
;     u32x4 nxt[NB][2];
;     const int r0 = wave * 32;
; #pragma unroll
;     for (int b = 0; b < NB; ++b)
; #pragma unroll
;         for (int j = 0; j < 2; ++j) nxt[b][j] = ((const u32x4*)(hb + (size_t)(r0 + b) * DM))[lane + 64 * j];
;     f32x4 gv[2][2], bv[2][2];
; #pragma unroll
;     for (int j = 0; j < 2; ++j)
; #pragma unroll
;         for (int q = 0; q < 2; ++q) { gv[j][q] = *(const f32x4*)(gam + 512 * j + 8 * lane + 4 * q); bv[j][q] = *(const f32x4*)(bet + 512 * j + 8 * lane + 4 * q); }
;     for (int it = 0; it < 32 / NB; ++it) {
;         const int r = r0 + it * NB;
;         float v[NB][16];
; #pragma unroll
;         for (int b = 0; b < NB; ++b)
; #pragma unroll
;             for (int j = 0; j < 2; ++j)
; #pragma unroll
;                 for (int k = 0; k < 4; ++k) { v[b][8 * j + 2 * k] = bflo(nxt[b][j][k]); v[b][8 * j + 2 * k + 1] = bfhi(nxt[b][j][k]); }
;         if (it + 1 < 32 / NB) {
; #pragma unroll
;             for (int b = 0; b < NB; ++b)
; #pragma unroll
;                 for (int j = 0; j < 2; ++j) nxt[b][j] = ((const u32x4*)(hb + (size_t)(r + NB + b) * DM))[lane + 64 * j];
;         }
;         float s[NB], s2[NB];
; #pragma unroll
;         for (int b = 0; b < NB; ++b) { s[b] = 0.f;
; #pragma unroll
;             for (int k = 0; k < 16; ++k) s[b] += v[b][k]; }
; #pragma unroll
;         for (int o = 1; o < 64; o <<= 1)
; #pragma unroll
;             for (int b = 0; b < NB; ++b) s[b] += __shfl_xor(s[b], o);
; #pragma unroll
;         for (int b = 0; b < NB; ++b) { const float mean = s[b] * (1.f / DM); s2[b] = 0.f;
; #pragma unroll
;             for (int k = 0; k < 16; ++k) { v[b][k] -= mean; s2[b] += v[b][k] * v[b][k]; } }
.LBB0_424:
	v_readlane_b32 s2, v249, 0
	v_readlane_b32 s3, v249, 1
	s_waitcnt vmcnt(0)
	s_barrier
	s_waitcnt lgkmcnt(0)
	s_barrier
	s_load_dwordx2 s[18:19], s[2:3], 0xf8
	s_load_dwordx4 s[8:11], s[2:3], 0xc0
	v_readlane_b32 s2, v249, 8
	v_readlane_b32 s3, v249, 9
	v_mov_b32_e32 v0, v189
	s_waitcnt lgkmcnt(0)
	s_add_u32 s1, s18, s2
	s_addc_u32 s2, s19, s3
	s_add_u32 s4, s1, 0x6000000
	s_addc_u32 s5, s2, 0
	v_readlane_b32 s2, v248, 38
	v_readlane_b32 s3, v248, 39
	s_lshl_b64 s[20:21], s[2:3], 2
	s_add_u32 s2, s8, s20
	s_addc_u32 s3, s9, s21
	s_add_u32 s26, s10, s20
	s_addc_u32 s27, s11, s21
	v_readfirstlane_b32 s1, v0
	s_ashr_i32 s8, s1, 1
	s_and_b32 s10, s8, 0xffffffe0
	s_ashr_i32 s11, s10, 31
	s_lshl_b64 s[38:39], s[10:11], 11
	v_and_b32_e32 v50, 63, v0
	s_add_u32 s40, s4, s38
	s_addc_u32 s41, s5, s39
	v_lshlrev_b32_e32 v0, 4, v50
	global_load_dwordx4 v[34:37], v0, s[40:41]
	global_load_dwordx4 v[38:41], v0, s[40:41] offset:1024
	s_or_b32 s40, s10, 1
	s_ashr_i32 s41, s40, 31
	s_lshl_b64 s[40:41], s[40:41], 11
	s_add_u32 s40, s4, s40
	s_addc_u32 s41, s5, s41
	v_lshlrev_b32_e32 v2, 5, v50
	global_load_dwordx4 v[42:45], v0, s[40:41]
	global_load_dwordx4 v[46:49], v0, s[40:41] offset:1024
	global_load_dwordx4 v[30:33], v2, s[2:3]
	global_load_dwordx4 v[26:29], v2, s[2:3] offset:16
	global_load_dwordx4 v[22:25], v2, s[26:27]
	global_load_dwordx4 v[18:21], v2, s[26:27] offset:16
	global_load_dwordx4 v[14:17], v2, s[2:3] offset:2048
	global_load_dwordx4 v[10:13], v2, s[2:3] offset:2064
	global_load_dwordx4 v[6:9], v2, s[26:27] offset:2048
	s_nop 0
	global_load_dwordx4 v[2:5], v2, s[26:27] offset:2064
	v_readlane_b32 s2, v249, 6
	v_readlane_b32 s3, v249, 7
	s_add_u32 s1, s18, s2
	s_addc_u32 s3, s19, s3
	s_add_u32 s2, s1, s38
	s_addc_u32 s3, s3, s39
	v_lshl_add_u64 v[52:53], s[2:3], 0, v[0:1]
	s_mov_b64 s[26:27], 0
	s_waitcnt vmcnt(0)
.LBB0_425:
	s_waitcnt vmcnt(4)
	v_lshlrev_b32_e32 v0, 16, v34
	v_and_b32_e32 v51, 0xffff0000, v34
	v_add_f32_e32 v86, 0, v0
	v_lshlrev_b32_e32 v56, 16, v35
	v_add_f32_e32 v86, v86, v51
	v_and_b32_e32 v57, 0xffff0000, v35
	v_add_f32_e32 v86, v86, v56
	v_lshlrev_b32_e32 v58, 16, v36
	v_add_f32_e32 v86, v86, v57
	v_and_b32_e32 v59, 0xffff0000, v36
	v_lshlrev_b32_e32 v70, 16, v42
	v_add_f32_e32 v86, v86, v58
	v_lshlrev_b32_e32 v60, 16, v37
	v_and_b32_e32 v71, 0xffff0000, v42
	v_add_f32_e32 v86, v86, v59
	v_add_f32_e32 v87, 0, v70
	v_and_b32_e32 v61, 0xffff0000, v37
	v_lshlrev_b32_e32 v72, 16, v43
	v_add_f32_e32 v86, v86, v60
	v_add_f32_e32 v87, v87, v71
	v_lshlrev_b32_e32 v62, 16, v38
	v_and_b32_e32 v73, 0xffff0000, v43
	v_add_f32_e32 v86, v86, v61
	v_add_f32_e32 v87, v87, v72
	v_and_b32_e32 v63, 0xffff0000, v38
	v_lshlrev_b32_e32 v74, 16, v44
	v_add_f32_e32 v86, v86, v62
	v_add_f32_e32 v87, v87, v73
	v_lshlrev_b32_e32 v64, 16, v39
	v_and_b32_e32 v75, 0xffff0000, v44
	v_add_f32_e32 v86, v86, v63
	v_add_f32_e32 v87, v87, v74
	v_and_b32_e32 v65, 0xffff0000, v39
	v_lshlrev_b32_e32 v76, 16, v45
	v_add_f32_e32 v86, v86, v64
	v_add_f32_e32 v87, v87, v75
	v_lshlrev_b32_e32 v66, 16, v40
	v_and_b32_e32 v77, 0xffff0000, v45
	v_add_f32_e32 v86, v86, v65
	v_add_f32_e32 v87, v87, v76
	v_and_b32_e32 v67, 0xffff0000, v40
	v_lshlrev_b32_e32 v78, 16, v46
	v_add_f32_e32 v86, v86, v66
	v_add_f32_e32 v87, v87, v77
	v_lshlrev_b32_e32 v68, 16, v41
	v_and_b32_e32 v79, 0xffff0000, v46
	v_add_f32_e32 v86, v86, v67
	v_add_f32_e32 v87, v87, v78
	v_and_b32_e32 v69, 0xffff0000, v41
	v_lshlrev_b32_e32 v80, 16, v47
	v_add_f32_e32 v86, v86, v68
	v_add_f32_e32 v87, v87, v79
	v_and_b32_e32 v81, 0xffff0000, v47
	v_add_f32_e32 v86, v86, v69
	v_add_f32_e32 v87, v87, v80
	v_lshlrev_b32_e32 v82, 16, v48
	v_add_f32_e32 v87, v87, v81
	v_and_b32_e32 v83, 0xffff0000, v48
	v_add_f32_e32 v87, v87, v82
	v_lshlrev_b32_e32 v84, 16, v49
	v_add_f32_e32 v87, v87, v83
	v_and_b32_e32 v85, 0xffff0000, v49
	v_add_f32_e32 v87, v87, v84
	v_add_f32_e32 v87, v87, v85
	s_waitcnt lgkmcnt(0)
	s_nop 1
	v_add_f32_dpp v86, v86, v86 quad_perm:[1,0,3,2] row_mask:0xf bank_mask:0xf
	v_lshl_add_u64 v[54:55], v[52:53], 0, s[26:27]
	s_mov_b32 s1, 0x6001000
	v_add_co_u32_e32 v46, vcc, s1, v54
	s_waitcnt lgkmcnt(0)
	s_nop 1
	v_add_f32_dpp v87, v87, v87 quad_perm:[1,0,3,2] row_mask:0xf bank_mask:0xf
	v_addc_co_u32_e32 v47, vcc, 0, v55, vcc
	global_load_dwordx4 v[34:37], v[46:47], off
	global_load_dwordx4 v[38:41], v[46:47], off offset:1024
	global_load_dwordx4 v[42:45], v[46:47], off offset:2048
	s_nop 0
	global_load_dwordx4 v[46:49], v[46:47], off offset:3072
	s_mov_b32 s1, 0x6000000
	s_waitcnt lgkmcnt(0)
	s_nop 1
	v_add_f32_dpp v86, v86, v86 quad_perm:[2,3,0,1] row_mask:0xf bank_mask:0xf
	s_add_u32 s26, s26, 0x1000
	s_addc_u32 s27, s27, 0
	s_cmpk_lg_u32 s26, 0xf000
	s_waitcnt lgkmcnt(0)
	s_nop 1
	v_add_f32_dpp v87, v87, v87 quad_perm:[2,3,0,1] row_mask:0xf bank_mask:0xf
	s_waitcnt lgkmcnt(0)
	s_nop 1
	v_add_f32_dpp v86, v86, v86 row_half_mirror row_mask:0xf bank_mask:0xf
	s_waitcnt lgkmcnt(0)
	s_nop 1
	v_add_f32_dpp v87, v87, v87 row_half_mirror row_mask:0xf bank_mask:0xf
	s_waitcnt lgkmcnt(0)
	s_nop 1
	v_add_f32_dpp v86, v86, v86 row_mirror row_mask:0xf bank_mask:0xf
	s_waitcnt lgkmcnt(0)
	s_nop 1
	v_add_f32_dpp v87, v87, v87 row_mirror row_mask:0xf bank_mask:0xf
	s_waitcnt lgkmcnt(0)
	s_waitcnt lgkmcnt(0)
	s_waitcnt lgkmcnt(0)
	s_nop 0
	v_readlane_b32 s98, v86, 0
	v_readlane_b32 s99, v86, 16
	v_readlane_b32 s100, v86, 32
	v_readlane_b32 s101, v86, 48
	v_mov_b32_e32 v86, s98
	v_add_f32_e32 v86, s99, v86
	v_mov_b32_e32 v88, s100
	v_add_f32_e32 v88, s101, v88
	v_add_f32_e32 v86, v86, v88
	v_fmac_f32_e32 v51, 0xba800000, v86
	v_fmac_f32_e32 v0, 0xba800000, v86
	v_fmac_f32_e32 v56, 0xba800000, v86
	v_fmac_f32_e32 v57, 0xba800000, v86
	s_waitcnt lgkmcnt(0)
; __device__ __forceinline__ unsigned pk2(float lo, float hi) { unsigned r; asm("v_cvt_pk_bf16_f32 %0, %1, %2" : "=v"(r) : "v"(lo), "v"(hi)); return r; }
; __device__ __forceinline__ void ln_panel_b(bf16_t* hb, float* outf, const float* gam, const float* bet) {
;     ...
;         for (int b = 0; b < NB; ++b) { const float mean = s[b] * (1.f / DM); s2[b] = 0.f;
; #pragma unroll
;             for (int k = 0; k < 16; ++k) { v[b][k] -= mean; s2[b] += v[b][k] * v[b][k]; } }
; #pragma unroll
;         for (int o = 1; o < 64; o <<= 1)
; #pragma unroll
;             for (int b = 0; b < NB; ++b) s2[b] += __shfl_xor(s2[b], o);
; #pragma unroll
;         for (int b = 0; b < NB; ++b) {
;             const float rstd = 1.f / sqrtf(s2[b] * (1.f / DM) + LN_EPS);
; #pragma unroll
;             for (int j = 0; j < 2; ++j) {
;                 float o[8];
; #pragma unroll
;                 for (int k = 0; k < 8; ++k) o[k] = v[b][8 * j + k] * rstd * gv[j][k >> 2][k & 3] + bv[j][k >> 2][k & 3];
;                 if (outf) { f32x4* op = (f32x4*)(outf + (size_t)(r + b) * DM + 512 * j + 8 * lane); op[0] = (f32x4){o[0], o[1], o[2], o[3]}; op[1] = (f32x4){o[4], o[5], o[6], o[7]}; }
;                 else { u32x4 w; w.x = pk2(o[0], o[1]); w.y = pk2(o[2], o[3]); w.z = pk2(o[4], o[5]); w.w = pk2(o[6], o[7]); ((u32x4*)(hb + (size_t)(r + b) * DM))[lane + 64 * j] = w; }
	s_nop 0
	v_readlane_b32 s98, v87, 0
	v_readlane_b32 s99, v87, 16
	v_readlane_b32 s100, v87, 32
	v_readlane_b32 s101, v87, 48
	v_mov_b32_e32 v87, s98
	v_add_f32_e32 v87, s99, v87
	v_mov_b32_e32 v88, s100
	v_add_f32_e32 v88, s101, v88
	v_add_f32_e32 v87, v87, v88
	v_mul_f32_e32 v88, v51, v51
	v_fmac_f32_e32 v88, v0, v0
	v_fmac_f32_e32 v88, v56, v56
	v_fmac_f32_e32 v88, v57, v57
	v_fmac_f32_e32 v58, 0xba800000, v86
	v_fmac_f32_e32 v88, v58, v58
	v_fmac_f32_e32 v59, 0xba800000, v86
	v_fmac_f32_e32 v71, 0xba800000, v87
	v_fmac_f32_e32 v88, v59, v59
	v_fmac_f32_e32 v60, 0xba800000, v86
	v_fmac_f32_e32 v61, 0xba800000, v86
	v_fmac_f32_e32 v62, 0xba800000, v86
	v_fmac_f32_e32 v63, 0xba800000, v86
	v_fmac_f32_e32 v64, 0xba800000, v86
	v_fmac_f32_e32 v65, 0xba800000, v86
	v_fmac_f32_e32 v66, 0xba800000, v86
	v_fmac_f32_e32 v67, 0xba800000, v86
	v_fmac_f32_e32 v68, 0xba800000, v86
	v_fmac_f32_e32 v69, 0xba800000, v86
	v_fmac_f32_e32 v70, 0xba800000, v87
	v_mul_f32_e32 v86, v71, v71
	v_fmac_f32_e32 v88, v60, v60
	v_fmac_f32_e32 v86, v70, v70
	v_fmac_f32_e32 v72, 0xba800000, v87
	v_fmac_f32_e32 v88, v61, v61
	v_fmac_f32_e32 v86, v72, v72
	v_fmac_f32_e32 v73, 0xba800000, v87
	v_fmac_f32_e32 v88, v62, v62
	v_fmac_f32_e32 v86, v73, v73
	v_fmac_f32_e32 v74, 0xba800000, v87
	v_fmac_f32_e32 v88, v63, v63
	v_fmac_f32_e32 v86, v74, v74
	v_fmac_f32_e32 v75, 0xba800000, v87
	v_fmac_f32_e32 v88, v64, v64
	v_fmac_f32_e32 v86, v75, v75
	v_fmac_f32_e32 v76, 0xba800000, v87
	v_fmac_f32_e32 v88, v65, v65
	v_fmac_f32_e32 v86, v76, v76
	v_fmac_f32_e32 v77, 0xba800000, v87
	v_fmac_f32_e32 v88, v66, v66
	v_fmac_f32_e32 v86, v77, v77
	v_fmac_f32_e32 v78, 0xba800000, v87
	v_fmac_f32_e32 v88, v67, v67
	v_fmac_f32_e32 v86, v78, v78
	v_fmac_f32_e32 v79, 0xba800000, v87
	v_fmac_f32_e32 v88, v68, v68
	v_fmac_f32_e32 v86, v79, v79
	v_fmac_f32_e32 v80, 0xba800000, v87
	v_fmac_f32_e32 v88, v69, v69
	v_fmac_f32_e32 v86, v80, v80
	v_fmac_f32_e32 v81, 0xba800000, v87
	v_fmac_f32_e32 v86, v81, v81
	v_fmac_f32_e32 v82, 0xba800000, v87
	v_fmac_f32_e32 v83, 0xba800000, v87
	v_fmac_f32_e32 v84, 0xba800000, v87
	v_fmac_f32_e32 v85, 0xba800000, v87
	v_fmac_f32_e32 v86, v82, v82
	v_fmac_f32_e32 v86, v83, v83
	v_fmac_f32_e32 v86, v84, v84
	v_fmac_f32_e32 v86, v85, v85
	s_waitcnt lgkmcnt(0)
	s_nop 1
	v_add_f32_dpp v87, v88, v88 quad_perm:[1,0,3,2] row_mask:0xf bank_mask:0xf
	s_waitcnt lgkmcnt(0)
	s_nop 1
	v_add_f32_dpp v86, v86, v86 quad_perm:[1,0,3,2] row_mask:0xf bank_mask:0xf
	s_waitcnt lgkmcnt(0)
	s_nop 1
	v_add_f32_dpp v87, v87, v87 quad_perm:[2,3,0,1] row_mask:0xf bank_mask:0xf
	s_waitcnt lgkmcnt(0)
	s_nop 1
	v_add_f32_dpp v86, v86, v86 quad_perm:[2,3,0,1] row_mask:0xf bank_mask:0xf
	s_waitcnt lgkmcnt(0)
	s_nop 1
	v_add_f32_dpp v87, v87, v87 row_half_mirror row_mask:0xf bank_mask:0xf
	s_waitcnt lgkmcnt(0)
	s_nop 1
	v_add_f32_dpp v86, v86, v86 row_half_mirror row_mask:0xf bank_mask:0xf
	s_waitcnt lgkmcnt(0)
	s_nop 1
	v_add_f32_dpp v87, v87, v87 row_mirror row_mask:0xf bank_mask:0xf
	s_waitcnt lgkmcnt(0)
	s_nop 1
	v_add_f32_dpp v86, v86, v86 row_mirror row_mask:0xf bank_mask:0xf
	s_waitcnt lgkmcnt(0)
	s_waitcnt lgkmcnt(0)
	s_waitcnt lgkmcnt(0)
	s_nop 0
	v_readlane_b32 s98, v87, 0
	v_readlane_b32 s99, v87, 16
	v_readlane_b32 s100, v87, 32
	v_readlane_b32 s101, v87, 48
	v_mov_b32_e32 v87, s98
	v_add_f32_e32 v87, s99, v87
	v_mov_b32_e32 v88, s100
	v_add_f32_e32 v88, s101, v88
	v_add_f32_e32 v87, v87, v88
	v_fmamk_f32 v87, v87, 0x3a800000, v231
	v_cmp_gt_f32_e32 vcc, s97, v87
	s_waitcnt lgkmcnt(0)
	s_nop 0
	v_readlane_b32 s98, v86, 0
	v_readlane_b32 s99, v86, 16
	v_readlane_b32 s100, v86, 32
	v_readlane_b32 s101, v86, 48
	v_mov_b32_e32 v86, s98
	v_add_f32_e32 v86, s99, v86
	v_mov_b32_e32 v88, s100
	v_add_f32_e32 v88, s101, v88
	v_add_f32_e32 v86, v86, v88
	v_mul_f32_e32 v88, 0x4f800000, v87
	v_cndmask_b32_e32 v87, v87, v88, vcc
	v_sqrt_f32_e32 v88, v87
	s_nop 0
	v_add_u32_e32 v89, -1, v88
	v_fma_f32 v90, -v89, v88, v87
	v_cmp_ge_f32_e64 s[2:3], 0, v90
	v_add_u32_e32 v90, 1, v88
	s_nop 0
	v_cndmask_b32_e64 v89, v88, v89, s[2:3]
	v_fma_f32 v88, -v90, v88, v87
	v_cmp_lt_f32_e64 s[2:3], 0, v88
	s_nop 1
	v_cndmask_b32_e64 v88, v89, v90, s[2:3]
	v_mul_f32_e32 v89, 0x37800000, v88
	v_cndmask_b32_e32 v88, v88, v89, vcc
	v_cmp_class_f32_e32 vcc, v87, v232
	s_nop 1
	v_cndmask_b32_e32 v87, v88, v87, vcc
	v_div_scale_f32 v88, s[2:3], v87, v87, 1.0
	v_rcp_f32_e32 v89, v88
	s_nop 0
	v_fma_f32 v90, -v88, v89, 1.0
	v_fmac_f32_e32 v89, v90, v89
	v_div_scale_f32 v90, vcc, 1.0, v87, 1.0
	v_mul_f32_e32 v91, v90, v89
	v_fma_f32 v92, -v88, v91, v90
	v_fmac_f32_e32 v91, v92, v89
	v_fma_f32 v88, -v88, v91, v90
	v_div_fmas_f32 v88, v88, v89, v91
	v_div_fixup_f32 v87, v88, v87, 1.0
	v_mul_f32_e32 v56, v56, v87
	v_fma_f32 v88, v32, v56, v24
	v_mul_f32_e32 v56, v57, v87
	v_fma_f32 v57, v33, v56, v25
	v_mul_f32_e32 v56, v58, v87
	v_fma_f32 v58, v26, v56, v18
	v_mul_f32_e32 v56, v59, v87
	v_fma_f32 v59, v27, v56, v19
	v_mul_f32_e32 v56, v60, v87
	v_fma_f32 v60, v28, v56, v20
	v_mul_f32_e32 v56, v61, v87
	v_mul_f32_e32 v0, v0, v87
	v_mul_f32_e32 v51, v51, v87
	v_fma_f32 v61, v29, v56, v21
	v_cvt_pk_bf16_f32 v58, v58, v59
	v_cvt_pk_bf16_f32 v59, v60, v61
	v_add_co_u32_e32 v60, vcc, s1, v54
	v_mul_f32_e32 v54, v64, v87
	v_fma_f32 v0, v30, v0, v22
	v_fma_f32 v51, v31, v51, v23
	v_cvt_pk_bf16_f32 v56, v0, v51
	v_addc_co_u32_e32 v61, vcc, 0, v55, vcc
	v_fma_f32 v55, v16, v54, v8
	v_mul_f32_e32 v54, v65, v87
	v_cvt_pk_bf16_f32 v57, v88, v57
	global_store_dwordx4 v[60:61], v[56:59], off
	v_mul_f32_e32 v0, v62, v87
	v_fma_f32 v0, v14, v0, v6
	v_fma_f32 v56, v17, v54, v9
	v_mul_f32_e32 v54, v66, v87
	v_fma_f32 v57, v10, v54, v2
; __device__ __forceinline__ unsigned pk2(float lo, float hi) { unsigned r; asm("v_cvt_pk_bf16_f32 %0, %1, %2" : "=v"(r) : "v"(lo), "v"(hi)); return r; }
; __device__ __forceinline__ void ln_panel_b(bf16_t* hb, float* outf, const float* gam, const float* bet) {
;     ...
;     for (int it = 0; it < 32 / NB; ++it) {
;         const int r = r0 + it * NB;
;         float v[NB][16];
; #pragma unroll
;         for (int b = 0; b < NB; ++b)
; #pragma unroll
;             for (int j = 0; j < 2; ++j)
; #pragma unroll
;                 for (int k = 0; k < 4; ++k) { v[b][8 * j + 2 * k] = bflo(nxt[b][j][k]); v[b][8 * j + 2 * k + 1] = bfhi(nxt[b][j][k]); }
;         if (it + 1 < 32 / NB) {
; #pragma unroll
;             for (int b = 0; b < NB; ++b)
; #pragma unroll
;                 for (int j = 0; j < 2; ++j) nxt[b][j] = ((const u32x4*)(hb + (size_t)(r + NB + b) * DM))[lane + 64 * j];
;         }
;         float s[NB], s2[NB];
; #pragma unroll
;         for (int b = 0; b < NB; ++b) { s[b] = 0.f;
; #pragma unroll
;             for (int k = 0; k < 16; ++k) s[b] += v[b][k]; }
; #pragma unroll
;         for (int o = 1; o < 64; o <<= 1)
; #pragma unroll
;             for (int b = 0; b < NB; ++b) s[b] += __shfl_xor(s[b], o);
; #pragma unroll
;         for (int b = 0; b < NB; ++b) { const float mean = s[b] * (1.f / DM); s2[b] = 0.f;
; #pragma unroll
;             for (int k = 0; k < 16; ++k) { v[b][k] -= mean; s2[b] += v[b][k] * v[b][k]; } }
; #pragma unroll
;         for (int o = 1; o < 64; o <<= 1)
; #pragma unroll
;             for (int b = 0; b < NB; ++b) s2[b] += __shfl_xor(s2[b], o);
; #pragma unroll
;         for (int b = 0; b < NB; ++b) {
;             const float rstd = 1.f / sqrtf(s2[b] * (1.f / DM) + LN_EPS);
; #pragma unroll
;             for (int j = 0; j < 2; ++j) {
;                 float o[8];
; #pragma unroll
;                 for (int k = 0; k < 8; ++k) o[k] = v[b][8 * j + k] * rstd * gv[j][k >> 2][k & 3] + bv[j][k >> 2][k & 3];
;                 if (outf) { f32x4* op = (f32x4*)(outf + (size_t)(r + b) * DM + 512 * j + 8 * lane); op[0] = (f32x4){o[0], o[1], o[2], o[3]}; op[1] = (f32x4){o[4], o[5], o[6], o[7]}; }
;                 else { u32x4 w; w.x = pk2(o[0], o[1]); w.y = pk2(o[2], o[3]); w.z = pk2(o[4], o[5]); w.w = pk2(o[6], o[7]); ((u32x4*)(hb + (size_t)(r + b) * DM))[lane + 64 * j] = w; }
;             }
	v_mul_f32_e32 v54, v67, v87
	v_fma_f32 v58, v11, v54, v3
	v_mul_f32_e32 v54, v68, v87
	v_mul_f32_e32 v51, v63, v87
	v_fma_f32 v59, v12, v54, v4
	v_mul_f32_e32 v54, v69, v87
	v_fma_f32 v51, v15, v51, v7
	v_fma_f32 v62, v13, v54, v5
	v_cvt_pk_bf16_f32 v54, v0, v51
	v_fmamk_f32 v0, v86, 0x3a800000, v231
	v_cmp_gt_f32_e32 vcc, s97, v0
	v_mul_f32_e32 v51, 0x4f800000, v0
	v_cvt_pk_bf16_f32 v55, v55, v56
	v_cvt_pk_bf16_f32 v56, v57, v58
	v_cvt_pk_bf16_f32 v57, v59, v62
	global_store_dwordx4 v[60:61], v[54:57], off offset:1024
	v_cndmask_b32_e32 v0, v0, v51, vcc
	v_sqrt_f32_e32 v51, v0
	s_nop 0
	v_add_u32_e32 v54, -1, v51
	v_fma_f32 v55, -v54, v51, v0
	v_cmp_ge_f32_e64 s[2:3], 0, v55
	v_add_u32_e32 v55, 1, v51
	s_nop 0
	v_cndmask_b32_e64 v54, v51, v54, s[2:3]
	v_fma_f32 v51, -v55, v51, v0
	v_cmp_lt_f32_e64 s[2:3], 0, v51
	s_nop 1
	v_cndmask_b32_e64 v51, v54, v55, s[2:3]
	v_mul_f32_e32 v54, 0x37800000, v51
	v_cndmask_b32_e32 v51, v51, v54, vcc
	v_cmp_class_f32_e32 vcc, v0, v232
	s_nop 1
	v_cndmask_b32_e32 v0, v51, v0, vcc
	v_div_scale_f32 v51, s[2:3], v0, v0, 1.0
	v_rcp_f32_e32 v54, v51
	s_nop 0
	v_fma_f32 v55, -v51, v54, 1.0
	v_fmac_f32_e32 v54, v55, v54
	v_div_scale_f32 v55, vcc, 1.0, v0, 1.0
	v_mul_f32_e32 v56, v55, v54
	v_fma_f32 v57, -v51, v56, v55
	v_fmac_f32_e32 v56, v57, v54
	v_fma_f32 v51, -v51, v56, v55
	v_div_fmas_f32 v51, v51, v54, v56
	v_div_fixup_f32 v0, v51, v0, 1.0
	v_mul_f32_e32 v54, v71, v0
	v_mul_f32_e32 v55, v72, v0
	v_mul_f32_e32 v56, v73, v0
	v_mul_f32_e32 v57, v74, v0
	v_mul_f32_e32 v51, v70, v0
	v_fma_f32 v54, v31, v54, v23
	v_fma_f32 v55, v32, v55, v24
	v_fma_f32 v56, v33, v56, v25
	v_fma_f32 v57, v26, v57, v18
	v_mul_f32_e32 v58, v75, v0
	v_mul_f32_e32 v59, v76, v0
	v_mul_f32_e32 v62, v77, v0
	v_fma_f32 v51, v30, v51, v22
	v_fma_f32 v58, v27, v58, v19
	v_fma_f32 v59, v28, v59, v20
	v_fma_f32 v62, v29, v62, v21
	v_cvt_pk_bf16_f32 v54, v51, v54
	v_cvt_pk_bf16_f32 v55, v55, v56
	v_cvt_pk_bf16_f32 v56, v57, v58
	v_cvt_pk_bf16_f32 v57, v59, v62
	global_store_dwordx4 v[60:61], v[54:57], off offset:2048
	v_mul_f32_e32 v51, v78, v0
	v_mul_f32_e32 v58, v83, v0
	v_mul_f32_e32 v54, v79, v0
	v_mul_f32_e32 v55, v80, v0
	v_mul_f32_e32 v56, v81, v0
	v_mul_f32_e32 v57, v82, v0
	v_fma_f32 v54, v15, v54, v7
	v_fma_f32 v55, v16, v55, v8
	v_fma_f32 v56, v17, v56, v9
	v_fma_f32 v57, v10, v57, v2
	v_mul_f32_e32 v59, v84, v0
	v_mul_f32_e32 v0, v85, v0
	v_fma_f32 v51, v14, v51, v6
	v_fma_f32 v58, v11, v58, v3
	v_fma_f32 v59, v12, v59, v4
	v_fma_f32 v0, v13, v0, v5
	v_cvt_pk_bf16_f32 v54, v51, v54
	v_cvt_pk_bf16_f32 v55, v55, v56
	v_cvt_pk_bf16_f32 v56, v57, v58
	v_cvt_pk_bf16_f32 v57, v59, v0
	global_store_dwordx4 v[60:61], v[54:57], off offset:3072
	s_cbranch_scc1 .LBB0_425
	s_waitcnt vmcnt(7)
	v_and_b32_e32 v65, 0xffff0000, v34
	v_lshlrev_b32_e32 v34, 16, v34
	v_add_f32_e32 v66, 0, v34
	v_and_b32_e32 v64, 0xffff0000, v35
	v_lshlrev_b32_e32 v35, 16, v35
	v_add_f32_e32 v66, v66, v65
	v_add_f32_e32 v66, v66, v35
	v_and_b32_e32 v63, 0xffff0000, v36
	v_lshlrev_b32_e32 v36, 16, v36
	v_add_f32_e32 v66, v66, v64
	s_waitcnt vmcnt(5)
	v_and_b32_e32 v57, 0xffff0000, v42
	v_lshlrev_b32_e32 v42, 16, v42
	v_add_f32_e32 v66, v66, v36
	v_and_b32_e32 v62, 0xffff0000, v37
	v_lshlrev_b32_e32 v37, 16, v37
	v_add_f32_e32 v66, v66, v63
	v_add_f32_e32 v67, 0, v42
	v_and_b32_e32 v56, 0xffff0000, v43
	v_lshlrev_b32_e32 v43, 16, v43
	v_add_f32_e32 v66, v66, v37
	v_add_f32_e32 v67, v67, v57
	v_and_b32_e32 v61, 0xffff0000, v38
	v_lshlrev_b32_e32 v38, 16, v38
	v_add_f32_e32 v66, v66, v62
	v_add_f32_e32 v67, v67, v43
	v_and_b32_e32 v55, 0xffff0000, v44
	v_lshlrev_b32_e32 v44, 16, v44
	v_add_f32_e32 v66, v66, v38
	v_add_f32_e32 v67, v67, v56
	v_and_b32_e32 v60, 0xffff0000, v39
	v_lshlrev_b32_e32 v39, 16, v39
	v_add_f32_e32 v66, v66, v61
	v_add_f32_e32 v67, v67, v44
	v_and_b32_e32 v54, 0xffff0000, v45
	v_lshlrev_b32_e32 v45, 16, v45
	v_add_f32_e32 v66, v66, v39
	v_add_f32_e32 v67, v67, v55
	v_and_b32_e32 v59, 0xffff0000, v40
	v_lshlrev_b32_e32 v40, 16, v40
	v_add_f32_e32 v66, v66, v60
	v_add_f32_e32 v67, v67, v45
	s_waitcnt vmcnt(4)
	v_and_b32_e32 v53, 0xffff0000, v46
	v_lshlrev_b32_e32 v46, 16, v46
	v_add_f32_e32 v66, v66, v40
	v_add_f32_e32 v67, v67, v54
	v_and_b32_e32 v58, 0xffff0000, v41
	v_lshlrev_b32_e32 v41, 16, v41
	v_add_f32_e32 v66, v66, v59
	v_add_f32_e32 v67, v67, v46
	v_and_b32_e32 v52, 0xffff0000, v47
	v_lshlrev_b32_e32 v47, 16, v47
	v_add_f32_e32 v66, v66, v41
	v_add_f32_e32 v67, v67, v53
	v_add_f32_e32 v66, v66, v58
	v_add_f32_e32 v67, v67, v47
	v_and_b32_e32 v51, 0xffff0000, v48
	v_lshlrev_b32_e32 v48, 16, v48
	v_add_f32_e32 v67, v67, v52
	v_add_f32_e32 v67, v67, v48
	v_and_b32_e32 v0, 0xffff0000, v49
	v_lshlrev_b32_e32 v49, 16, v49
	v_add_f32_e32 v67, v67, v51
	v_add_f32_e32 v67, v67, v49
	v_add_f32_e32 v67, v67, v0
	s_waitcnt lgkmcnt(0)
	s_nop 1
	v_add_f32_dpp v66, v66, v66 quad_perm:[1,0,3,2] row_mask:0xf bank_mask:0xf
	s_or_b32 s10, s10, 30
	s_ashr_i32 s11, s10, 31
	v_lshlrev_b32_e32 v50, 4, v50
	s_movk_i32 s42, 0x400
	s_waitcnt lgkmcnt(0)
	s_nop 1
	v_add_f32_dpp v67, v67, v67 quad_perm:[1,0,3,2] row_mask:0xf bank_mask:0xf
	v_mov_b32_e32 v131, v1
	v_mov_b32_e32 v135, v1
	v_mov_b32_e32 v133, v1
	s_waitcnt lgkmcnt(0)
	s_nop 1
	v_add_f32_dpp v66, v66, v66 quad_perm:[2,3,0,1] row_mask:0xf bank_mask:0xf
	s_waitcnt lgkmcnt(0)
	s_nop 1
	v_add_f32_dpp v67, v67, v67 quad_perm:[2,3,0,1] row_mask:0xf bank_mask:0xf
	s_waitcnt lgkmcnt(0)
	s_nop 1
	v_add_f32_dpp v66, v66, v66 row_half_mirror row_mask:0xf bank_mask:0xf
	s_waitcnt lgkmcnt(0)
	s_nop 1
	v_add_f32_dpp v67, v67, v67 row_half_mirror row_mask:0xf bank_mask:0xf
	s_waitcnt lgkmcnt(0)
; __device__ __forceinline__ void ln_panel_b(bf16_t* hb, float* outf, const float* gam, const float* bet) {
;     ...
; #pragma unroll
;         for (int o = 1; o < 64; o <<= 1)
; #pragma unroll
;             for (int b = 0; b < NB; ++b) s[b] += __shfl_xor(s[b], o);
; #pragma unroll
;         for (int b = 0; b < NB; ++b) { const float mean = s[b] * (1.f / DM); s2[b] = 0.f;
; #pragma unroll
;             for (int k = 0; k < 16; ++k) { v[b][k] -= mean; s2[b] += v[b][k] * v[b][k]; } }
; #pragma unroll
;         for (int o = 1; o < 64; o <<= 1)
; #pragma unroll
;             for (int b = 0; b < NB; ++b) s2[b] += __shfl_xor(s2[b], o);
; #pragma unroll
;         for (int b = 0; b < NB; ++b) {
;             const float rstd = 1.f / sqrtf(s2[b] * (1.f / DM) + LN_EPS);
; #pragma unroll
;             for (int j = 0; j < 2; ++j) {
;                 float o[8];
; #pragma unroll
;                 for (int k = 0; k < 8; ++k) o[k] = v[b][8 * j + k] * rstd * gv[j][k >> 2][k & 3] + bv[j][k >> 2][k & 3];
	s_nop 1
	v_add_f32_dpp v66, v66, v66 row_mirror row_mask:0xf bank_mask:0xf
	s_waitcnt lgkmcnt(0)
	s_nop 1
	v_add_f32_dpp v67, v67, v67 row_mirror row_mask:0xf bank_mask:0xf
	s_waitcnt lgkmcnt(0)
	s_waitcnt lgkmcnt(0)
	s_waitcnt lgkmcnt(0)
	s_nop 0
	v_readlane_b32 s98, v66, 0
	v_readlane_b32 s99, v66, 16
	v_readlane_b32 s100, v66, 32
	v_readlane_b32 s101, v66, 48
	v_mov_b32_e32 v66, s98
	v_add_f32_e32 v66, s99, v66
	v_mov_b32_e32 v68, s100
	v_add_f32_e32 v68, s101, v68
	v_add_f32_e32 v66, v66, v68
	v_fmac_f32_e32 v65, 0xba800000, v66
	v_fmac_f32_e32 v34, 0xba800000, v66
	v_fmac_f32_e32 v35, 0xba800000, v66
	v_fmac_f32_e32 v64, 0xba800000, v66
	s_waitcnt lgkmcnt(0)
	s_nop 0
	v_readlane_b32 s98, v67, 0
	v_readlane_b32 s99, v67, 16
	v_readlane_b32 s100, v67, 32
	v_readlane_b32 s101, v67, 48
	v_mov_b32_e32 v67, s98
	v_add_f32_e32 v67, s99, v67
	v_mov_b32_e32 v68, s100
	v_add_f32_e32 v68, s101, v68
	v_add_f32_e32 v67, v67, v68
	v_mul_f32_e32 v68, v65, v65
	v_fmac_f32_e32 v68, v34, v34
	v_fmac_f32_e32 v68, v35, v35
	v_fmac_f32_e32 v68, v64, v64
	v_fmac_f32_e32 v36, 0xba800000, v66
	v_fmac_f32_e32 v68, v36, v36
	v_fmac_f32_e32 v63, 0xba800000, v66
	v_fmac_f32_e32 v57, 0xba800000, v67
	v_fmac_f32_e32 v68, v63, v63
	v_fmac_f32_e32 v37, 0xba800000, v66
	v_fmac_f32_e32 v62, 0xba800000, v66
	v_fmac_f32_e32 v38, 0xba800000, v66
	v_fmac_f32_e32 v61, 0xba800000, v66
	v_fmac_f32_e32 v39, 0xba800000, v66
	v_fmac_f32_e32 v60, 0xba800000, v66
	v_fmac_f32_e32 v40, 0xba800000, v66
	v_fmac_f32_e32 v59, 0xba800000, v66
	v_fmac_f32_e32 v41, 0xba800000, v66
	v_fmac_f32_e32 v58, 0xba800000, v66
	v_fmac_f32_e32 v42, 0xba800000, v67
	v_mul_f32_e32 v66, v57, v57
	v_fmac_f32_e32 v68, v37, v37
	v_fmac_f32_e32 v66, v42, v42
	v_fmac_f32_e32 v43, 0xba800000, v67
	v_fmac_f32_e32 v68, v62, v62
	v_fmac_f32_e32 v66, v43, v43
	v_fmac_f32_e32 v56, 0xba800000, v67
	v_fmac_f32_e32 v68, v38, v38
	v_fmac_f32_e32 v66, v56, v56
	v_fmac_f32_e32 v44, 0xba800000, v67
	v_fmac_f32_e32 v68, v61, v61
	v_fmac_f32_e32 v66, v44, v44
	v_fmac_f32_e32 v55, 0xba800000, v67
	v_fmac_f32_e32 v68, v39, v39
	v_fmac_f32_e32 v66, v55, v55
	v_fmac_f32_e32 v45, 0xba800000, v67
	v_fmac_f32_e32 v68, v60, v60
	v_fmac_f32_e32 v66, v45, v45
	v_fmac_f32_e32 v54, 0xba800000, v67
	v_fmac_f32_e32 v68, v40, v40
	v_fmac_f32_e32 v66, v54, v54
	v_fmac_f32_e32 v46, 0xba800000, v67
	v_fmac_f32_e32 v68, v59, v59
	v_fmac_f32_e32 v66, v46, v46
	v_fmac_f32_e32 v53, 0xba800000, v67
	v_fmac_f32_e32 v68, v41, v41
	v_fmac_f32_e32 v66, v53, v53
	v_fmac_f32_e32 v47, 0xba800000, v67
	v_fmac_f32_e32 v68, v58, v58
	v_fmac_f32_e32 v66, v47, v47
	v_fmac_f32_e32 v52, 0xba800000, v67
	v_fmac_f32_e32 v66, v52, v52
	v_fmac_f32_e32 v48, 0xba800000, v67
	v_fmac_f32_e32 v51, 0xba800000, v67
	v_fmac_f32_e32 v49, 0xba800000, v67
	v_fmac_f32_e32 v0, 0xba800000, v67
	v_fmac_f32_e32 v66, v48, v48
	v_fmac_f32_e32 v66, v51, v51
	v_fmac_f32_e32 v66, v49, v49
	v_fmac_f32_e32 v66, v0, v0
	s_waitcnt lgkmcnt(0)
	s_nop 1
	v_add_f32_dpp v67, v68, v68 quad_perm:[1,0,3,2] row_mask:0xf bank_mask:0xf
	s_waitcnt lgkmcnt(0)
	s_nop 1
	v_add_f32_dpp v66, v66, v66 quad_perm:[1,0,3,2] row_mask:0xf bank_mask:0xf
	s_waitcnt lgkmcnt(0)
	s_nop 1
	v_add_f32_dpp v67, v67, v67 quad_perm:[2,3,0,1] row_mask:0xf bank_mask:0xf
	s_waitcnt lgkmcnt(0)
	s_nop 1
	v_add_f32_dpp v66, v66, v66 quad_perm:[2,3,0,1] row_mask:0xf bank_mask:0xf
	s_waitcnt lgkmcnt(0)
	s_nop 1
	v_add_f32_dpp v67, v67, v67 row_half_mirror row_mask:0xf bank_mask:0xf
	s_waitcnt lgkmcnt(0)
	s_nop 1
	v_add_f32_dpp v66, v66, v66 row_half_mirror row_mask:0xf bank_mask:0xf
	s_waitcnt lgkmcnt(0)
	s_nop 1
	v_add_f32_dpp v67, v67, v67 row_mirror row_mask:0xf bank_mask:0xf
	s_waitcnt lgkmcnt(0)
	s_nop 1
	v_add_f32_dpp v66, v66, v66 row_mirror row_mask:0xf bank_mask:0xf
	s_waitcnt lgkmcnt(0)
	s_waitcnt lgkmcnt(0)
	s_waitcnt lgkmcnt(0)
	s_nop 0
	v_readlane_b32 s98, v67, 0
	v_readlane_b32 s99, v67, 16
	v_readlane_b32 s100, v67, 32
	v_readlane_b32 s101, v67, 48
	v_mov_b32_e32 v67, s98
	v_add_f32_e32 v67, s99, v67
	v_mov_b32_e32 v68, s100
	v_add_f32_e32 v68, s101, v68
	v_add_f32_e32 v67, v67, v68
	v_fmamk_f32 v67, v67, 0x3a800000, v231
	v_cmp_gt_f32_e32 vcc, s97, v67
	s_waitcnt lgkmcnt(0)
	s_nop 0
	v_readlane_b32 s98, v66, 0
	v_readlane_b32 s99, v66, 16
	v_readlane_b32 s100, v66, 32
	v_readlane_b32 s101, v66, 48
	v_mov_b32_e32 v66, s98
	v_add_f32_e32 v66, s99, v66
	v_mov_b32_e32 v68, s100
	v_add_f32_e32 v68, s101, v68
	v_add_f32_e32 v66, v66, v68
	v_mul_f32_e32 v68, 0x4f800000, v67
	v_cndmask_b32_e32 v67, v67, v68, vcc
	v_sqrt_f32_e32 v68, v67
	s_nop 0
	v_add_u32_e32 v69, -1, v68
	v_fma_f32 v70, -v69, v68, v67
	v_cmp_ge_f32_e64 s[2:3], 0, v70
	v_add_u32_e32 v70, 1, v68
	s_nop 0
	v_cndmask_b32_e64 v69, v68, v69, s[2:3]
	v_fma_f32 v68, -v70, v68, v67
	v_cmp_lt_f32_e64 s[2:3], 0, v68
	s_nop 1
	v_cndmask_b32_e64 v68, v69, v70, s[2:3]
	v_mul_f32_e32 v69, 0x37800000, v68
	v_cndmask_b32_e32 v68, v68, v69, vcc
	v_cmp_class_f32_e32 vcc, v67, v232
	s_nop 1
	v_cndmask_b32_e32 v67, v68, v67, vcc
	v_div_scale_f32 v68, s[2:3], v67, v67, 1.0
	v_rcp_f32_e32 v69, v68
	s_lshl_b64 s[2:3], s[10:11], 11
	s_add_u32 s2, s4, s2
	s_addc_u32 s3, s5, s3
	v_fma_f32 v70, -v68, v69, 1.0
	v_fmac_f32_e32 v69, v70, v69
	v_div_scale_f32 v70, vcc, 1.0, v67, 1.0
	v_mul_f32_e32 v71, v70, v69
	v_fma_f32 v72, -v68, v71, v70
	v_fmac_f32_e32 v71, v72, v69
	v_fma_f32 v68, -v68, v71, v70
	v_div_fmas_f32 v68, v68, v69, v71
	v_div_fixup_f32 v67, v68, v67, 1.0
	v_mul_f32_e32 v34, v34, v67
	v_fma_f32 v34, v30, v34, v22
	v_mul_f32_e32 v65, v65, v67
	v_mul_f32_e32 v35, v35, v67
	v_mul_f32_e32 v36, v36, v67
	v_mul_f32_e32 v37, v37, v67
	v_fma_f32 v65, v31, v65, v23
; __device__ __forceinline__ unsigned pk2(float lo, float hi) { unsigned r; asm("v_cvt_pk_bf16_f32 %0, %1, %2" : "=v"(r) : "v"(lo), "v"(hi)); return r; }
; __device__ __forceinline__ void block_fence() { __builtin_amdgcn_fence(__ATOMIC_RELEASE, "workgroup"); __syncthreads(); __builtin_amdgcn_fence(__ATOMIC_ACQUIRE, "workgroup"); }
; __device__ __forceinline__ void ln_panel_b(bf16_t* hb, float* outf, const float* gam, const float* bet) {
;     ...
;         for (int b = 0; b < NB; ++b) {
;             const float rstd = 1.f / sqrtf(s2[b] * (1.f / DM) + LN_EPS);
; #pragma unroll
;             for (int j = 0; j < 2; ++j) {
;                 float o[8];
; #pragma unroll
;                 for (int k = 0; k < 8; ++k) o[k] = v[b][8 * j + k] * rstd * gv[j][k >> 2][k & 3] + bv[j][k >> 2][k & 3];
;                 if (outf) { f32x4* op = (f32x4*)(outf + (size_t)(r + b) * DM + 512 * j + 8 * lane); op[0] = (f32x4){o[0], o[1], o[2], o[3]}; op[1] = (f32x4){o[4], o[5], o[6], o[7]}; }
;                 else { u32x4 w; w.x = pk2(o[0], o[1]); w.y = pk2(o[2], o[3]); w.z = pk2(o[4], o[5]); w.w = pk2(o[6], o[7]); ((u32x4*)(hb + (size_t)(r + b) * DM))[lane + 64 * j] = w; }
;             }
	v_fma_f32 v35, v32, v35, v24
	v_mul_f32_e32 v64, v64, v67
	v_fma_f32 v36, v26, v36, v18
	v_mul_f32_e32 v63, v63, v67
	v_fma_f32 v37, v28, v37, v20
	v_mul_f32_e32 v62, v62, v67
	v_cvt_pk_bf16_f32 v34, v34, v65
	v_fma_f32 v64, v33, v64, v25
	v_fma_f32 v63, v27, v63, v19
	v_fma_f32 v62, v29, v62, v21
	v_cvt_pk_bf16_f32 v35, v35, v64
	v_cvt_pk_bf16_f32 v36, v36, v63
	v_cvt_pk_bf16_f32 v37, v37, v62
	global_store_dwordx4 v50, v[34:37], s[2:3]
	s_nop 1
	v_mul_f32_e32 v34, v38, v67
	v_fma_f32 v34, v14, v34, v6
	v_mul_f32_e32 v35, v61, v67
	v_mul_f32_e32 v36, v39, v67
	v_mul_f32_e32 v37, v60, v67
	v_fma_f32 v35, v15, v35, v7
	v_fma_f32 v36, v16, v36, v8
	v_fma_f32 v37, v17, v37, v9
	v_mul_f32_e32 v38, v40, v67
	v_mul_f32_e32 v39, v59, v67
	v_mul_f32_e32 v40, v41, v67
	v_mul_f32_e32 v41, v58, v67
	v_cvt_pk_bf16_f32 v34, v34, v35
	v_fma_f32 v38, v10, v38, v2
	v_fma_f32 v39, v11, v39, v3
	v_fma_f32 v40, v12, v40, v4
	v_fma_f32 v41, v13, v41, v5
	v_cvt_pk_bf16_f32 v35, v36, v37
	v_cvt_pk_bf16_f32 v36, v38, v39
	v_cvt_pk_bf16_f32 v37, v40, v41
	global_store_dwordx4 v50, v[34:37], s[2:3] offset:1024
	s_nop 1
	v_fmamk_f32 v34, v66, 0x3a800000, v231
	v_cmp_gt_f32_e32 vcc, s97, v34
	v_mul_f32_e32 v35, 0x4f800000, v34
	s_nop 0
	v_cndmask_b32_e32 v34, v34, v35, vcc
	v_sqrt_f32_e32 v35, v34
	s_nop 0
	v_add_u32_e32 v36, -1, v35
	v_fma_f32 v37, -v36, v35, v34
	v_cmp_ge_f32_e64 s[2:3], 0, v37
	v_add_u32_e32 v37, 1, v35
	s_nop 0
	v_cndmask_b32_e64 v36, v35, v36, s[2:3]
	v_fma_f32 v35, -v37, v35, v34
	v_cmp_lt_f32_e64 s[2:3], 0, v35
	s_nop 1
	v_cndmask_b32_e64 v35, v36, v37, s[2:3]
	v_mul_f32_e32 v36, 0x37800000, v35
	v_cndmask_b32_e32 v35, v35, v36, vcc
	v_cmp_class_f32_e32 vcc, v34, v232
	s_nop 1
	v_cndmask_b32_e32 v34, v35, v34, vcc
	v_div_scale_f32 v35, s[2:3], v34, v34, 1.0
	v_rcp_f32_e32 v36, v35
	s_or_b32 s2, s8, 31
	s_ashr_i32 s3, s2, 31
	s_lshl_b64 s[2:3], s[2:3], 11
	v_fma_f32 v37, -v35, v36, 1.0
	v_fmac_f32_e32 v36, v37, v36
	v_div_scale_f32 v37, vcc, 1.0, v34, 1.0
	v_mul_f32_e32 v38, v37, v36
	v_fma_f32 v39, -v35, v38, v37
	v_fmac_f32_e32 v38, v39, v36
	v_fma_f32 v35, -v35, v38, v37
	v_div_fmas_f32 v35, v35, v36, v38
	v_div_fixup_f32 v34, v35, v34, 1.0
	v_mul_f32_e32 v35, v42, v34
	v_fma_f32 v22, v30, v35, v22
	v_mul_f32_e32 v30, v57, v34
	v_fma_f32 v23, v31, v30, v23
	v_mul_f32_e32 v30, v43, v34
	v_fma_f32 v24, v32, v30, v24
	v_mul_f32_e32 v30, v56, v34
	v_fmac_f32_e32 v25, v33, v30
	v_mul_f32_e32 v30, v44, v34
	v_fma_f32 v26, v26, v30, v18
	v_mul_f32_e32 v18, v55, v34
	v_fma_f32 v27, v27, v18, v19
	v_mul_f32_e32 v18, v45, v34
	s_add_u32 s2, s4, s2
	v_fma_f32 v28, v28, v18, v20
	v_mul_f32_e32 v18, v54, v34
	s_addc_u32 s3, s5, s3
	v_fmac_f32_e32 v21, v29, v18
	v_cvt_pk_bf16_f32 v18, v22, v23
	v_cvt_pk_bf16_f32 v19, v24, v25
	v_cvt_pk_bf16_f32 v20, v26, v27
	v_cvt_pk_bf16_f32 v21, v28, v21
	global_store_dwordx4 v50, v[18:21], s[2:3]
	v_mul_f32_e32 v0, v0, v34
	v_fmac_f32_e32 v5, v13, v0
	v_mul_f32_e32 v18, v46, v34
	v_fma_f32 v6, v14, v18, v6
	v_mul_f32_e32 v14, v53, v34
	v_fma_f32 v7, v15, v14, v7
	v_mul_f32_e32 v14, v47, v34
	v_fma_f32 v8, v16, v14, v8
	v_mul_f32_e32 v14, v52, v34
	v_fmac_f32_e32 v9, v17, v14
	v_mul_f32_e32 v14, v48, v34
	v_fma_f32 v10, v10, v14, v2
	v_mul_f32_e32 v2, v51, v34
	v_fma_f32 v11, v11, v2, v3
	v_mul_f32_e32 v2, v49, v34
	v_fma_f32 v12, v12, v2, v4
	v_cvt_pk_bf16_f32 v2, v6, v7
	v_cvt_pk_bf16_f32 v3, v8, v9
	v_cvt_pk_bf16_f32 v4, v10, v11
	v_cvt_pk_bf16_f32 v5, v12, v5
	global_store_dwordx4 v50, v[2:5], s[2:3] offset:1024
	v_readlane_b32 s2, v249, 0
	v_readlane_b32 s3, v249, 1
	v_mov_b32_e32 v15, v189
	s_barrier
; #define PG8_STAGE(bufoff, gbase, voff) do { _Pragma("unroll") for (int _i = 0; _i < 2; ++_i) \
;         __builtin_amdgcn_global_load_lds((const unsigned*)((const char*)(gbase) + (voff)[_i]), (LAS unsigned*)(lds + (bufoff) + ldsw + _i * 8192), 16, 0, 0); } while (0)
; #define PG8_WAIT_V(n) asm volatile("s_waitcnt vmcnt(" #n ")" ::: "memory")
; #define PG8_BAR __builtin_amdgcn_s_barrier()
; template <class Epi, class Sched>
; __device__ __forceinline__ void gemm_phase(LAS unsigned char* lds, const Gemm g, const Sched& S, const Epi& E) {
;     ...
;     for (int i = 0; i < 2; ++i) { int R, C; stage_rc(tid * 16 + i * 8192, R, C); const int Rb = Epi::PERM ? ((R & ~31) + perm32(R & 31)) : R;
;         voffA[i] = (unsigned)(R * K + C) * 2u; voffB[i] = (unsigned)(Rb * K + C) * 2u; }
;     const size_t kstep = (size_t)(BK * 2);
;     const size_t hstep = (size_t)HALF * K * 2;
;     const size_t tstep = 2 * hstep;
;     const unsigned ldsw = (unsigned)wid * 1024u;
;     const int aoff = lds_byte(wr * 64 + fr, fq * 8), boff = lds_byte(wc * 32 + fr, fq * 8);
;     ...
;     Unit cur, nxt; int ui = 0;
;     if (!S.next(0, cur)) return;
;     f32x4 acc[2][2][4][2];
; #pragma unroll
;     for (int a = 0; a < 2; ++a)
; #pragma unroll
;         for (int b = 0; b < 2; ++b)
; #pragma unroll
;             for (int m = 0; m < 4; ++m)
; #pragma unroll
;                 for (int n = 0; n < 2; ++n) acc[a][b][m][n] = (f32x4){0.f, 0.f, 0.f, 0.f};
;     bf16x8 At[4][2], B0[2][2], B1[2][2];
;     const char* cA = (const char*)g.A + (size_t)cur.pm * tstep; const char* cB = (const char*)g.Bt + (size_t)cur.pn * tstep;
;     S.a_ready(cur);
;     PG8_STAGE(PG8_SB(0, 0), cB, voffB); PG8_STAGE(PG8_SB(0, 1), cB + hstep, voffB); PG8_STAGE(PG8_SA(0, 0), cA, voffA); PG8_STAGE(PG8_SA(0, 1), cA + hstep, voffA);
;     if (wr == 1) PG8_BAR;
;     PG8_WAIT_V(2); PG8_BAR;
;     PG8_STAGE(PG8_SB(1, 0), cB + kstep, voffB); PG8_STAGE(PG8_SA(1, 0), cA + kstep, voffA); PG8_STAGE(PG8_SB(1, 1), cB + hstep + kstep, voffB);
;     PG8_WAIT_V(6); PG8_BAR;
	s_load_dwordx2 s[46:47], s[2:3], 0xf8
	v_readlane_b32 s2, v249, 8
	v_lshlrev_b32_e32 v0, 4, v15
	v_add_u32_e32 v2, 0x2000, v0
	v_ashrrev_i32_e32 v3, 31, v2
	v_lshrrev_b32_e32 v3, 22, v3
	v_add_u32_e32 v3, v2, v3
	v_ashrrev_i32_e32 v3, 10, v3
	v_mul_i32_i24_e32 v4, 0x400, v3
	v_sub_u32_e32 v2, v2, v4
	v_lshrrev_b32_e32 v4, 4, v2
	v_readlane_b32 s3, v249, 9
	s_waitcnt lgkmcnt(0)
	s_add_u32 s1, s46, s2
	v_bitop3_b32 v2, v4, v2, 32 bitop3:0x6c
	s_addc_u32 s3, s47, s3
	v_readlane_b32 s4, v248, 36
	v_ashrrev_i32_e32 v4, 31, v2
	s_add_u32 s2, s1, 0x6000000
	v_readlane_b32 s5, v248, 37
	v_lshrrev_b32_e32 v4, 26, v4
	s_addc_u32 s3, s3, 0
	s_lshl_b64 s[10:11], s[4:5], 23
	v_add_u32_e32 v4, v2, v4
	v_lshlrev_b32_e32 v6, 3, v3
	s_add_u32 s1, s46, s10
	v_ashrrev_i32_e32 v5, 6, v4
	v_and_b32_e32 v6, -16, v6
	v_lshlrev_b32_e32 v3, 5, v3
	s_addc_u32 s4, s47, s11
	v_add_u32_e32 v6, v5, v6
	v_and_b32_e32 v14, 32, v3
	v_and_b32_e32 v3, 0xc0, v4
	s_add_u32 s18, s1, 0x1000000
	v_and_b32_e32 v5, 3, v5
	s_mov_b32 s1, 0x7fffffe0
	v_lshrrev_b32_e32 v7, 2, v6
	v_lshlrev_b32_e32 v8, 1, v6
	v_sub_u32_e32 v2, v2, v3
	v_and_or_b32 v5, v6, s1, v5
	v_and_b32_e32 v7, 4, v7
	v_and_b32_e32 v8, 24, v8
	v_ashrrev_i16_sdwa v2, v227, sext(v2) dst_sel:DWORD dst_unused:UNUSED_PAD src0_sel:DWORD src1_sel:BYTE_0
	v_or3_b32 v5, v5, v7, v8
	v_bfe_i32 v16, v2, 0, 16
	v_add_u32_e32 v2, v14, v16
	v_mul_lo_u32 v5, v5, s42
	v_mul_lo_u32 v17, v6, s42
	v_add_lshl_u32 v130, v5, v2, 1
	v_add_lshl_u32 v132, v2, v17, 1
	v_bfe_i32 v2, v15, 27, 1
	v_lshrrev_b32_e32 v2, 22, v2
	v_add_u32_e32 v2, v0, v2
	v_and_b32_e32 v2, 0xfffffc00, v2
	v_sub_u32_e32 v0, v0, v2
	v_lshrrev_b32_e32 v2, 4, v0
	v_ashrrev_i32_e32 v4, 31, v15
	v_bitop3_b32 v0, v2, v0, 32 bitop3:0x6c
	v_lshrrev_b32_e32 v4, 26, v4
	v_ashrrev_i32_e32 v2, 31, v0
	v_add_u32_e32 v4, v15, v4
	v_lshrrev_b32_e32 v2, 26, v2
	v_ashrrev_i32_e32 v4, 6, v4
	v_add_u32_e32 v2, v0, v2
	v_lshlrev_b32_e32 v5, 3, v4
	v_ashrrev_i32_e32 v3, 6, v2
	v_and_b32_e32 v5, -16, v5
	v_add_u32_e32 v5, v3, v5
	v_and_b32_e32 v2, 0xc0, v2
	v_readfirstlane_b32 s8, v15
	v_and_b32_e32 v3, 3, v3
	v_lshrrev_b32_e32 v6, 2, v5
	v_lshlrev_b32_e32 v7, 1, v5
	v_sub_u32_e32 v0, v0, v2
	s_addc_u32 s19, s4, 0
	s_ashr_i32 s9, s8, 6
	v_and_or_b32 v3, v5, s1, v3
	v_and_b32_e32 v6, 4, v6
	v_and_b32_e32 v7, 24, v7
	v_lshlrev_b32_e32 v4, 5, v4
	v_ashrrev_i16_sdwa v0, v227, sext(v0) dst_sel:DWORD dst_unused:UNUSED_PAD src0_sel:DWORD src1_sel:BYTE_0
	s_lshl_b32 s4, s9, 10
	v_or3_b32 v3, v3, v6, v7
	v_and_b32_e32 v18, 32, v4
	v_bfe_i32 v19, v0, 0, 16
	v_mul_lo_u32 v3, v3, s42
	v_add_u32_e32 v2, v18, v19
	s_add_i32 s5, s4, 0
	s_ashr_i32 s43, s42, 31
	v_add_lshl_u32 v0, v3, v2, 1
	s_add_i32 m0, s5, 0x10000
	s_ashr_i32 s36, s8, 8
	s_lshl_b64 s[26:27], s[42:43], 8
	global_load_lds_dwordx4 v0, s[18:19]
	s_add_i32 m0, s5, 0x12000
	s_add_u32 s38, s18, s26
	global_load_lds_dwordx4 v130, s[18:19]
	s_addc_u32 s39, s19, s27
	s_add_i32 m0, s5, 0x14000
	v_mul_lo_u32 v20, v5, s42
	global_load_lds_dwordx4 v0, s[38:39]
	s_add_i32 m0, s5, 0x16000
	s_add_i32 s54, s5, 0x2000
	v_add_lshl_u32 v134, v2, v20, 1
	v_lshl_add_u64 v[6:7], s[38:39], 0, v[0:1]
	v_lshl_add_u64 v[8:9], s[38:39], 0, v[130:131]
	global_load_lds_dwordx4 v130, s[38:39]
	s_mov_b32 m0, s5
	s_add_u32 s38, s2, s26
	global_load_lds_dwordx4 v134, s[2:3]
	s_mov_b32 m0, s54
	s_addc_u32 s39, s3, s27
	s_add_i32 s55, s5, 0x4000
	global_load_lds_dwordx4 v132, s[2:3]
	s_mov_b32 m0, s55
	s_add_i32 s56, s5, 0x6000
	global_load_lds_dwordx4 v134, s[38:39]
	s_mov_b32 m0, s56
	s_cmp_eq_u32 s36, 1
	global_load_lds_dwordx4 v132, s[38:39]
	v_lshl_add_u64 v[2:3], s[18:19], 0, v[0:1]
	v_lshl_add_u64 v[4:5], s[18:19], 0, v[130:131]
	v_lshl_add_u64 v[10:11], s[2:3], 0, v[134:135]
	v_lshl_add_u64 v[12:13], s[2:3], 0, v[132:133]
	s_cselect_b64 s[38:39], -1, 0
	s_cmp_lg_u32 s36, 1
	s_cbranch_scc1 .LBB0_428
	s_barrier

; __device__ __forceinline__ float bflo(unsigned w) { return __uint_as_float(w << 16); }
; __device__ __forceinline__ float bfhi(unsigned w) { return __uint_as_float(w & 0xffff0000u); }
; __device__ __forceinline__ void ln_panel_b(bf16_t* hb, float* outf, const float* gam, const float* bet) {
;     int tid_ = threadIdx.x; asm volatile("" : "+v"(tid_));
;     const int lane = tid_ & 63, wave = __builtin_amdgcn_readfirstlane(tid_ >> 6);
;     constexpr int NB = 2;
;     u32x4 nxt[NB][2];
;     const int r0 = wave * 32;
; #pragma unroll
;     for (int b = 0; b < NB; ++b)
; #pragma unroll
;         for (int j = 0; j < 2; ++j) nxt[b][j] = ((const u32x4*)(hb + (size_t)(r0 + b) * DM))[lane + 64 * j];
;     f32x4 gv[2][2], bv[2][2];
; #pragma unroll
;     for (int j = 0; j < 2; ++j)
; #pragma unroll
;         for (int q = 0; q < 2; ++q) { gv[j][q] = *(const f32x4*)(gam + 512 * j + 8 * lane + 4 * q); bv[j][q] = *(const f32x4*)(bet + 512 * j + 8 * lane + 4 * q); }
;     for (int it = 0; it < 32 / NB; ++it) {
;         const int r = r0 + it * NB;
;         float v[NB][16];
; #pragma unroll
;         for (int b = 0; b < NB; ++b)
; #pragma unroll
;             for (int j = 0; j < 2; ++j)
; #pragma unroll
;                 for (int k = 0; k < 4; ++k) { v[b][8 * j + 2 * k] = bflo(nxt[b][j][k]); v[b][8 * j + 2 * k + 1] = bfhi(nxt[b][j][k]); }
;         if (it + 1 < 32 / NB) {
; #pragma unroll
;             for (int b = 0; b < NB; ++b)
; #pragma unroll
;                 for (int j = 0; j < 2; ++j) nxt[b][j] = ((const u32x4*)(hb + (size_t)(r + NB + b) * DM))[lane + 64 * j];
;         }
;         float s[NB], s2[NB];
; #pragma unroll
;         for (int b = 0; b < NB; ++b) { s[b] = 0.f;
; #pragma unroll
;             for (int k = 0; k < 16; ++k) s[b] += v[b][k]; }
; #pragma unroll
;         for (int o = 1; o < 64; o <<= 1)
; #pragma unroll
;             for (int b = 0; b < NB; ++b) s[b] += __shfl_xor(s[b], o);
.LBB0_456:
	v_readlane_b32 s2, v249, 0
	v_readlane_b32 s3, v249, 1
	s_waitcnt vmcnt(0)
	s_barrier
	s_waitcnt lgkmcnt(0)
	s_barrier
	s_load_dwordx8 s[40:47], s[2:3], 0xe0
	v_readlane_b32 s2, v249, 8
	v_readlane_b32 s3, v249, 9
	v_mov_b32_e32 v0, v189
	s_waitcnt lgkmcnt(0)
	s_add_u32 s1, s46, s2
	s_addc_u32 s2, s47, s3
	s_add_u32 s4, s1, 0x6000000
	s_addc_u32 s5, s2, 0
	v_readlane_b32 s2, v249, 4
	v_readlane_b32 s3, v249, 5
	s_lshl_b64 s[2:3], s[2:3], 2
	s_add_u32 s1, s44, s2
	s_addc_u32 s8, s45, s3
	v_readlane_b32 s2, v248, 32
	v_readlane_b32 s3, v248, 33
	s_and_b64 s[2:3], s[2:3], exec
	s_cselect_b32 s11, s8, 0
	s_cselect_b32 s10, s1, 0
	s_add_u32 s2, s40, s20
	s_addc_u32 s3, s41, s21
	s_add_u32 s8, s42, s20
	v_readfirstlane_b32 s1, v0
	s_addc_u32 s9, s43, s21
	s_ashr_i32 s36, s1, 1
	s_and_b32 s18, s36, 0xffffffe0
	s_ashr_i32 s19, s18, 31
	s_lshl_b64 s[38:39], s[18:19], 11
	v_and_b32_e32 v66, 63, v0
	s_add_u32 s20, s4, s38
	s_addc_u32 s21, s5, s39
	v_lshlrev_b32_e32 v0, 4, v66
	global_load_dwordx4 v[50:53], v0, s[20:21]
	global_load_dwordx4 v[62:65], v0, s[20:21] offset:1024
	s_or_b32 s20, s18, 1
	s_ashr_i32 s21, s20, 31
	s_lshl_b64 s[20:21], s[20:21], 11
	s_add_u32 s20, s4, s20
	s_addc_u32 s21, s5, s21
	v_lshlrev_b32_e32 v34, 5, v66
	global_load_dwordx4 v[54:57], v0, s[20:21]
	global_load_dwordx4 v[58:61], v0, s[20:21] offset:1024
	global_load_dwordx4 v[26:29], v34, s[2:3]
	global_load_dwordx4 v[18:21], v34, s[2:3] offset:16
	global_load_dwordx4 v[30:33], v34, s[8:9]
	global_load_dwordx4 v[22:25], v34, s[8:9] offset:16
	global_load_dwordx4 v[10:13], v34, s[2:3] offset:2048
	global_load_dwordx4 v[2:5], v34, s[2:3] offset:2064
	global_load_dwordx4 v[14:17], v34, s[8:9] offset:2048
	global_load_dwordx4 v[6:9], v34, s[8:9] offset:2064
	s_cmp_lg_u64 s[10:11], 0
	v_readlane_b32 s2, v249, 6
	s_cselect_b64 s[26:27], -1, 0
	v_readlane_b32 s3, v249, 7
	s_add_u32 s1, s46, s2
	s_addc_u32 s3, s47, s3
	s_add_u32 s2, s1, s38
	s_addc_u32 s3, s3, s39
	v_lshl_add_u64 v[70:71], s[2:3], 0, v[0:1]
	s_lshl_b64 s[2:3], s[18:19], 12
	s_add_u32 s2, s10, s2
	v_mov_b32_e32 v35, v1
	s_addc_u32 s3, s11, s3
	v_lshl_add_u64 v[34:35], s[2:3], 0, v[34:35]
	s_mov_b64 s[2:3], 0x1000
	v_lshlrev_b32_e32 v68, 3, v66
	s_mov_b64 s[20:21], 0
	v_lshl_add_u64 v[72:73], v[34:35], 0, s[2:3]
	s_waitcnt vmcnt(0)
	s_branch .LBB0_458
.LBB0_457:
	s_add_u32 s20, s20, 0x1000
	s_addc_u32 s21, s21, 0
	s_mov_b64 s[8:9], 0x2000
	s_waitcnt vmcnt(7)
	v_mov_b64_e32 v[52:53], v[36:37]
	s_waitcnt vmcnt(6)
	v_mov_b64_e32 v[64:65], v[48:49]
	s_waitcnt vmcnt(5)
	v_mov_b64_e32 v[56:57], v[40:41]
	s_waitcnt vmcnt(4)
	v_mov_b64_e32 v[60:61], v[44:45]
	v_lshl_add_u64 v[72:73], v[72:73], 0, s[8:9]
	s_cmpk_eq_u32 s20, 0xf000
	v_mov_b64_e32 v[50:51], v[34:35]
	v_mov_b64_e32 v[62:63], v[46:47]
	v_mov_b64_e32 v[54:55], v[38:39]
	v_mov_b64_e32 v[58:59], v[42:43]
	s_cbranch_scc1 .LBB0_474
.LBB0_458:
	v_lshlrev_b32_e32 v76, 16, v54
	v_and_b32_e32 v77, 0xffff0000, v54
	v_add_f32_e32 v0, 0, v76
	v_add_f32_e32 v0, v0, v77
	v_lshlrev_b32_e32 v54, 16, v55
	v_and_b32_e32 v55, 0xffff0000, v55
	v_add_f32_e32 v0, v0, v54
	v_lshlrev_b32_e32 v86, 16, v64
	v_and_b32_e32 v87, 0xffff0000, v64
	v_lshlrev_b32_e32 v84, 16, v65
	v_and_b32_e32 v85, 0xffff0000, v65
	v_lshlrev_b32_e32 v90, 16, v62
	v_and_b32_e32 v91, 0xffff0000, v62
	v_lshlrev_b32_e32 v88, 16, v63
	v_and_b32_e32 v89, 0xffff0000, v63
	v_lshlrev_b32_e32 v62, 16, v60
	v_and_b32_e32 v63, 0xffff0000, v60
	v_lshlrev_b32_e32 v64, 16, v61
	v_and_b32_e32 v65, 0xffff0000, v61
	v_lshlrev_b32_e32 v60, 16, v58
	v_and_b32_e32 v61, 0xffff0000, v58
	v_lshlrev_b32_e32 v58, 16, v56
	v_add_f32_e32 v0, v0, v55
	v_lshlrev_b32_e32 v92, 16, v59
	v_and_b32_e32 v93, 0xffff0000, v59
	v_and_b32_e32 v59, 0xffff0000, v56
	v_add_f32_e32 v0, v0, v58
	v_lshlrev_b32_e32 v56, 16, v57
	v_add_f32_e32 v0, v0, v59
	v_and_b32_e32 v57, 0xffff0000, v57
	v_add_f32_e32 v0, v0, v56
	v_add_f32_e32 v0, v0, v57
	v_add_f32_e32 v0, v0, v60
	v_add_f32_e32 v0, v0, v61
	v_add_f32_e32 v0, v0, v92
	v_add_f32_e32 v0, v0, v93
	v_add_f32_e32 v0, v0, v62
	v_add_f32_e32 v0, v0, v63
	v_add_f32_e32 v0, v0, v64
	v_add_f32_e32 v0, v0, v65
	v_lshl_add_u64 v[74:75], v[70:71], 0, s[20:21]
	v_add_co_u32_e32 v42, vcc, 0x6001000, v74
	s_waitcnt lgkmcnt(0)
	s_nop 1
	v_add_f32_dpp v0, v0, v0 quad_perm:[1,0,3,2] row_mask:0xf bank_mask:0xf
	v_addc_co_u32_e32 v43, vcc, 0, v75, vcc
	global_load_dwordx4 v[34:37], v[42:43], off
	global_load_dwordx4 v[46:49], v[42:43], off offset:1024
	global_load_dwordx4 v[38:41], v[42:43], off offset:2048
	s_nop 0
	global_load_dwordx4 v[42:45], v[42:43], off offset:3072
	s_waitcnt lgkmcnt(0)
	s_nop 1
	v_add_f32_dpp v0, v0, v0 quad_perm:[2,3,0,1] row_mask:0xf bank_mask:0xf
	s_waitcnt lgkmcnt(0)
	s_nop 1
	v_add_f32_dpp v0, v0, v0 row_half_mirror row_mask:0xf bank_mask:0xf
	s_waitcnt lgkmcnt(0)
	s_nop 1
	v_add_f32_dpp v0, v0, v0 row_mirror row_mask:0xf bank_mask:0xf
	s_waitcnt lgkmcnt(0)
	s_waitcnt lgkmcnt(0)
; __device__ __forceinline__ void ln_panel_b(bf16_t* hb, float* outf, const float* gam, const float* bet) {
;     ...
;         float s[NB], s2[NB];
; #pragma unroll
;         for (int b = 0; b < NB; ++b) { s[b] = 0.f;
; #pragma unroll
;             for (int k = 0; k < 16; ++k) s[b] += v[b][k]; }
; #pragma unroll
;         for (int o = 1; o < 64; o <<= 1)
; #pragma unroll
;             for (int b = 0; b < NB; ++b) s[b] += __shfl_xor(s[b], o);
; #pragma unroll
;         for (int b = 0; b < NB; ++b) { const float mean = s[b] * (1.f / DM); s2[b] = 0.f;
; #pragma unroll
;             for (int k = 0; k < 16; ++k) { v[b][k] -= mean; s2[b] += v[b][k] * v[b][k]; } }
; #pragma unroll
;         for (int o = 1; o < 64; o <<= 1)
; #pragma unroll
;             for (int b = 0; b < NB; ++b) s2[b] += __shfl_xor(s2[b], o);
	s_nop 0
	v_readlane_b32 s98, v0, 0
	v_readlane_b32 s99, v0, 16
	v_readlane_b32 s100, v0, 32
	v_readlane_b32 s101, v0, 48
	v_mov_b32_e32 v0, s98
	v_add_f32_e32 v0, s99, v0
	v_mov_b32_e32 v67, s100
	v_add_f32_e32 v67, s101, v67
	v_add_f32_e32 v0, v0, v67
	v_mul_f32_e32 v0, 0x3a800000, v0
	v_pk_add_f32 v[76:77], v[76:77], v[0:1] op_sel_hi:[1,0] neg_lo:[0,1] neg_hi:[0,1]
	v_pk_add_f32 v[78:79], v[54:55], v[0:1] op_sel_hi:[1,0] neg_lo:[0,1] neg_hi:[0,1]
	v_pk_mul_f32 v[94:95], v[76:77], v[76:77]
	v_pk_mul_f32 v[54:55], v[78:79], v[78:79]
	v_pk_add_f32 v[80:81], v[58:59], v[0:1] op_sel_hi:[1,0] neg_lo:[0,1] neg_hi:[0,1]
	v_pk_add_f32 v[82:83], v[56:57], v[0:1] op_sel_hi:[1,0] neg_lo:[0,1] neg_hi:[0,1]
	v_pk_add_f32 v[58:59], v[60:61], v[0:1] op_sel_hi:[1,0] neg_lo:[0,1] neg_hi:[0,1]
	v_pk_add_f32 v[60:61], v[92:93], v[0:1] op_sel_hi:[1,0] neg_lo:[0,1] neg_hi:[0,1]
	v_pk_add_f32 v[62:63], v[62:63], v[0:1] op_sel_hi:[1,0] neg_lo:[0,1] neg_hi:[0,1]
	v_pk_add_f32 v[64:65], v[64:65], v[0:1] op_sel_hi:[1,0] neg_lo:[0,1] neg_hi:[0,1]
	v_add_f32_e32 v0, v94, v95
	v_add_f32_e32 v0, v54, v0
	v_pk_mul_f32 v[96:97], v[80:81], v[80:81]
	v_add_f32_e32 v0, v55, v0
	v_add_f32_e32 v0, v96, v0
	v_pk_mul_f32 v[56:57], v[82:83], v[82:83]
	v_add_f32_e32 v0, v97, v0
	v_add_f32_e32 v0, v56, v0
	v_pk_mul_f32 v[98:99], v[58:59], v[58:59]
	v_add_f32_e32 v0, v57, v0
	v_add_f32_e32 v0, v98, v0
	v_pk_mul_f32 v[92:93], v[60:61], v[60:61]
	v_add_f32_e32 v0, v99, v0
	v_add_f32_e32 v0, v92, v0
	v_pk_mul_f32 v[100:101], v[62:63], v[62:63]
	v_add_f32_e32 v0, v93, v0
	v_add_f32_e32 v0, v100, v0
	v_pk_mul_f32 v[102:103], v[64:65], v[64:65]
	v_add_f32_e32 v0, v101, v0
	v_add_f32_e32 v0, v102, v0
	v_add_f32_e32 v0, v103, v0
	v_lshlrev_b32_e32 v56, 16, v50
	v_and_b32_e32 v57, 0xffff0000, v50
	v_add_f32_e32 v50, 0, v56
	v_add_f32_e32 v69, v50, v57
	s_waitcnt lgkmcnt(0)
	s_nop 1
	v_add_f32_dpp v0, v0, v0 quad_perm:[1,0,3,2] row_mask:0xf bank_mask:0xf
	v_lshlrev_b32_e32 v50, 16, v51
	v_and_b32_e32 v51, 0xffff0000, v51
	v_add_f32_e32 v69, v69, v50
	v_add_f32_e32 v69, v69, v51
	s_waitcnt lgkmcnt(0)
	s_nop 1
	v_add_f32_dpp v0, v0, v0 quad_perm:[2,3,0,1] row_mask:0xf bank_mask:0xf
	v_and_b32_e32 v55, 0xffff0000, v52
	s_waitcnt lgkmcnt(0)
	s_nop 1
	v_add_f32_dpp v0, v0, v0 row_half_mirror row_mask:0xf bank_mask:0xf
	s_waitcnt lgkmcnt(0)
	s_nop 1
	v_add_f32_dpp v0, v0, v0 row_mirror row_mask:0xf bank_mask:0xf
	s_waitcnt lgkmcnt(0)
	v_lshlrev_b32_e32 v54, 16, v52
	v_add_f32_e32 v69, v69, v54
	v_lshlrev_b32_e32 v52, 16, v53
	v_add_f32_e32 v69, v69, v55
	v_and_b32_e32 v53, 0xffff0000, v53
	v_add_f32_e32 v69, v69, v52
	v_add_f32_e32 v69, v69, v53
	v_add_f32_e32 v69, v69, v90
	v_add_f32_e32 v69, v69, v91
	v_add_f32_e32 v69, v69, v88
	v_add_f32_e32 v69, v69, v89
	v_add_f32_e32 v69, v69, v86
	v_add_f32_e32 v69, v69, v87
	v_add_f32_e32 v69, v69, v84
	v_add_f32_e32 v69, v69, v85
	s_waitcnt lgkmcnt(1)
	s_nop 1
	v_add_f32_dpp v69, v69, v69 quad_perm:[1,0,3,2] row_mask:0xf bank_mask:0xf
	s_waitcnt lgkmcnt(0)
	s_nop 1
	v_add_f32_dpp v69, v69, v69 quad_perm:[2,3,0,1] row_mask:0xf bank_mask:0xf
	s_waitcnt lgkmcnt(0)
	s_nop 1
	v_add_f32_dpp v69, v69, v69 row_half_mirror row_mask:0xf bank_mask:0xf
	s_waitcnt lgkmcnt(0)
	s_nop 1
	v_add_f32_dpp v69, v69, v69 row_mirror row_mask:0xf bank_mask:0xf
	s_waitcnt lgkmcnt(0)
	s_waitcnt lgkmcnt(0)
; __device__ __forceinline__ unsigned pk2(float lo, float hi) { unsigned r; asm("v_cvt_pk_bf16_f32 %0, %1, %2" : "=v"(r) : "v"(lo), "v"(hi)); return r; }
; __device__ __forceinline__ void ln_panel_b(bf16_t* hb, float* outf, const float* gam, const float* bet) {
;     ...
;         for (int o = 1; o < 64; o <<= 1)
; #pragma unroll
;             for (int b = 0; b < NB; ++b) s2[b] += __shfl_xor(s2[b], o);
; #pragma unroll
;         for (int b = 0; b < NB; ++b) {
;             const float rstd = 1.f / sqrtf(s2[b] * (1.f / DM) + LN_EPS);
; #pragma unroll
;             for (int j = 0; j < 2; ++j) {
;                 float o[8];
; #pragma unroll
;                 for (int k = 0; k < 8; ++k) o[k] = v[b][8 * j + k] * rstd * gv[j][k >> 2][k & 3] + bv[j][k >> 2][k & 3];
;                 if (outf) { f32x4* op = (f32x4*)(outf + (size_t)(r + b) * DM + 512 * j + 8 * lane); op[0] = (f32x4){o[0], o[1], o[2], o[3]}; op[1] = (f32x4){o[4], o[5], o[6], o[7]}; }
;                 else { u32x4 w; w.x = pk2(o[0], o[1]); w.y = pk2(o[2], o[3]); w.z = pk2(o[4], o[5]); w.w = pk2(o[6], o[7]); ((u32x4*)(hb + (size_t)(r + b) * DM))[lane + 64 * j] = w; }
	s_nop 0
	v_readlane_b32 s98, v69, 0
	v_readlane_b32 s99, v69, 16
	v_readlane_b32 s100, v69, 32
	v_readlane_b32 s101, v69, 48
	v_mov_b32_e32 v69, s98
	v_add_f32_e32 v69, s99, v69
	v_mov_b32_e32 v92, s100
	v_add_f32_e32 v92, s101, v92
	v_add_f32_e32 v69, v69, v92
	v_mul_f32_e32 v92, 0x3a800000, v69
	v_pk_add_f32 v[56:57], v[56:57], v[92:93] op_sel_hi:[1,0] neg_lo:[0,1] neg_hi:[0,1]
	v_pk_add_f32 v[50:51], v[50:51], v[92:93] op_sel_hi:[1,0] neg_lo:[0,1] neg_hi:[0,1]
	v_pk_mul_f32 v[94:95], v[56:57], v[56:57]
	v_pk_mul_f32 v[96:97], v[50:51], v[50:51]
	v_add_f32_e32 v69, v94, v95
	v_pk_add_f32 v[98:99], v[54:55], v[92:93] op_sel_hi:[1,0] neg_lo:[0,1] neg_hi:[0,1]
	v_add_f32_e32 v69, v96, v69
	v_pk_mul_f32 v[54:55], v[98:99], v[98:99]
	v_add_f32_e32 v69, v97, v69
	v_pk_add_f32 v[52:53], v[52:53], v[92:93] op_sel_hi:[1,0] neg_lo:[0,1] neg_hi:[0,1]
	v_add_f32_e32 v54, v54, v69
	v_pk_mul_f32 v[100:101], v[52:53], v[52:53]
	v_add_f32_e32 v54, v55, v54
	v_pk_add_f32 v[90:91], v[90:91], v[92:93] op_sel_hi:[1,0] neg_lo:[0,1] neg_hi:[0,1]
	v_add_f32_e32 v54, v100, v54
	v_pk_mul_f32 v[102:103], v[90:91], v[90:91]
	v_add_f32_e32 v54, v101, v54
	v_pk_add_f32 v[88:89], v[88:89], v[92:93] op_sel_hi:[1,0] neg_lo:[0,1] neg_hi:[0,1]
	v_add_f32_e32 v54, v102, v54
	v_pk_mul_f32 v[104:105], v[88:89], v[88:89]
	v_add_f32_e32 v54, v103, v54
	v_pk_add_f32 v[86:87], v[86:87], v[92:93] op_sel_hi:[1,0] neg_lo:[0,1] neg_hi:[0,1]
	v_add_f32_e32 v54, v104, v54
	v_pk_mul_f32 v[106:107], v[86:87], v[86:87]
	v_add_f32_e32 v54, v105, v54
	v_pk_add_f32 v[84:85], v[84:85], v[92:93] op_sel_hi:[1,0] neg_lo:[0,1] neg_hi:[0,1]
	v_add_f32_e32 v54, v106, v54
	v_pk_mul_f32 v[92:93], v[84:85], v[84:85]
	v_add_f32_e32 v54, v107, v54
	v_add_f32_e32 v54, v92, v54
	v_add_f32_e32 v54, v93, v54
	s_waitcnt lgkmcnt(0)
	s_nop 1
	v_add_f32_dpp v54, v54, v54 quad_perm:[1,0,3,2] row_mask:0xf bank_mask:0xf
	s_waitcnt lgkmcnt(0)
	s_nop 1
	v_add_f32_dpp v54, v54, v54 quad_perm:[2,3,0,1] row_mask:0xf bank_mask:0xf
	s_waitcnt lgkmcnt(0)
	s_nop 1
	v_add_f32_dpp v54, v54, v54 row_half_mirror row_mask:0xf bank_mask:0xf
	s_waitcnt lgkmcnt(0)
	s_nop 1
	v_add_f32_dpp v54, v54, v54 row_mirror row_mask:0xf bank_mask:0xf
	s_waitcnt lgkmcnt(0)
	s_waitcnt lgkmcnt(0)
	s_nop 0
	v_readlane_b32 s98, v54, 0
	v_readlane_b32 s99, v54, 16
	v_readlane_b32 s100, v54, 32
	v_readlane_b32 s101, v54, 48
	v_mov_b32_e32 v54, s98
	v_add_f32_e32 v54, s99, v54
	v_mov_b32_e32 v55, s100
	v_add_f32_e32 v55, s101, v55
	v_add_f32_e32 v54, v54, v55
	v_fmamk_f32 v54, v54, 0x3a800000, v231
	v_cmp_gt_f32_e32 vcc, s97, v54
	v_mul_f32_e32 v55, 0x4f800000, v54
	s_nop 0
	v_cndmask_b32_e32 v54, v54, v55, vcc
	v_sqrt_f32_e32 v55, v54
	s_nop 0
	v_add_u32_e32 v69, -1, v55
	v_fma_f32 v92, -v69, v55, v54
	v_cmp_ge_f32_e64 s[2:3], 0, v92
	v_add_u32_e32 v92, 1, v55
	s_nop 0
	v_cndmask_b32_e64 v69, v55, v69, s[2:3]
	v_fma_f32 v55, -v92, v55, v54
	v_cmp_lt_f32_e64 s[2:3], 0, v55
	s_nop 1
	v_cndmask_b32_e64 v55, v69, v92, s[2:3]
	v_mul_f32_e32 v69, 0x37800000, v55
	v_cndmask_b32_e32 v55, v55, v69, vcc
	v_cmp_class_f32_e32 vcc, v54, v232
	s_nop 1
	v_cndmask_b32_e32 v54, v55, v54, vcc
	v_div_scale_f32 v55, s[2:3], v54, v54, 1.0
	v_rcp_f32_e32 v69, v55
	s_nop 0
	v_fma_f32 v92, -v55, v69, 1.0
	v_fmac_f32_e32 v69, v92, v69
	v_div_scale_f32 v92, vcc, 1.0, v54, 1.0
	v_mul_f32_e32 v93, v92, v69
	v_fma_f32 v94, -v55, v93, v92
	v_fmac_f32_e32 v93, v94, v69
	v_fma_f32 v55, -v55, v93, v92
	v_div_fmas_f32 v55, v55, v69, v93
	v_div_fixup_f32 v92, v55, v54, 1.0
	v_pk_mul_f32 v[50:51], v[50:51], v[92:93] op_sel_hi:[1,0]
	v_pk_mul_f32 v[54:55], v[56:57], v[92:93] op_sel_hi:[1,0]
	v_pk_fma_f32 v[56:57], v[28:29], v[50:51], v[32:33]
	v_pk_mul_f32 v[50:51], v[98:99], v[92:93] op_sel_hi:[1,0]
	v_pk_mul_f32 v[52:53], v[52:53], v[92:93] op_sel_hi:[1,0]
	v_cndmask_b32_e64 v69, 0, 1, s[26:27]
	v_pk_fma_f32 v[54:55], v[26:27], v[54:55], v[30:31]
	v_pk_fma_f32 v[50:51], v[18:19], v[50:51], v[22:23]
	v_pk_fma_f32 v[52:53], v[20:21], v[52:53], v[24:25]
	v_cmp_ne_u32_e64 s[2:3], 1, v69
	s_andn2_b64 vcc, exec, s[26:27]
	s_cbranch_vccnz .LBB0_469
	global_store_dwordx4 v[72:73], v[54:57], off offset:-4096
	global_store_dwordx4 v[72:73], v[50:53], off offset:-4080
	s_cbranch_execnz .LBB0_461
